# GEMV inner loop: k-pair packed FMA without register shuffles, weight loads issued four iterations ahead
# baseline (speedup 1.0000x reference)
; __device__ __forceinline__ void phase_prologue(const Params& p, uchar* sm) {
;     ...
;         float acc[16];
; #pragma unroll
;         for (int b = 0; b < 16; ++b) acc[b] = 0.f;
;         const float* wp = p.ada_w + (size_t)(w * 128) * NMODV + col;
; #pragma unroll 4
;         for (int k = 0; k < 128; ++k) { const float wv = wp[(size_t)k * NMODV];
; #pragma unroll
;             for (int b = 0; b < 16; ++b) acc[b] += sc[b * 1024 + w * 128 + k] * wv; }
.LBB0_32:
	v_ashrrev_i32_e32 v47, 31, v46
	v_lshl_add_u64 v[48:49], v[46:47], 2, v[44:45]
	s_mov_b64 s[2:3], 0
	v_mov_b32_e32 v47, v66
	v_mov_b32_e32 v156, 0
	v_mov_b32_e32 v157, 0
	v_mov_b32_e32 v158, 0
	v_mov_b32_e32 v159, 0
	v_mov_b32_e32 v160, 0
	v_mov_b32_e32 v161, 0
	v_mov_b32_e32 v162, 0
	v_mov_b32_e32 v163, 0
	v_mov_b32_e32 v164, 0
	v_mov_b32_e32 v165, 0
	v_mov_b32_e32 v166, 0
	v_mov_b32_e32 v167, 0
	v_mov_b32_e32 v168, 0
	v_mov_b32_e32 v169, 0
	v_mov_b32_e32 v170, 0
	v_mov_b32_e32 v171, 0
	v_mov_b32_e32 v172, 0
	v_mov_b32_e32 v173, 0
	v_mov_b32_e32 v174, 0
	v_mov_b32_e32 v175, 0
	v_mov_b32_e32 v176, 0
	v_mov_b32_e32 v177, 0
	v_mov_b32_e32 v178, 0
	v_mov_b32_e32 v179, 0
	v_mov_b32_e32 v180, 0
	v_mov_b32_e32 v181, 0
	v_mov_b32_e32 v182, 0
	v_mov_b32_e32 v183, 0
	v_mov_b32_e32 v184, 0
	v_mov_b32_e32 v185, 0
	v_mov_b32_e32 v186, 0
	v_mov_b32_e32 v187, 0
	v_lshl_add_u64 v[96:97], v[48:49], 0, s[2:3]
	v_add_co_u32_e64 v98, s[4:5], s9, v96
	s_nop 1
	v_addc_co_u32_e64 v99, s[4:5], 0, v97, s[4:5]
	global_load_dword v100, v[96:97], off
	v_add_co_u32_e64 v120, s[4:5], s11, v96
	s_nop 1
	v_addc_co_u32_e64 v121, s[4:5], 0, v97, s[4:5]
	v_add_co_u32_e64 v96, s[4:5], s12, v96
	s_nop 1
	v_addc_co_u32_e64 v97, s[4:5], 0, v97, s[4:5]
	global_load_dword v101, v[98:99], off
	global_load_dword v102, v[120:121], off
	global_load_dword v103, v[96:97], off
	s_add_u32 s2, s2, 0x60000
	s_addc_u32 s3, s3, 0
	v_lshl_add_u64 v[96:97], v[48:49], 0, s[2:3]
	v_add_co_u32_e64 v98, s[4:5], s9, v96
	s_nop 1
	v_addc_co_u32_e64 v99, s[4:5], 0, v97, s[4:5]
	global_load_dword v104, v[96:97], off
	v_add_co_u32_e64 v120, s[4:5], s11, v96
	s_nop 1
	v_addc_co_u32_e64 v121, s[4:5], 0, v97, s[4:5]
	v_add_co_u32_e64 v96, s[4:5], s12, v96
	s_nop 1
	v_addc_co_u32_e64 v97, s[4:5], 0, v97, s[4:5]
	global_load_dword v105, v[98:99], off
	global_load_dword v106, v[120:121], off
	global_load_dword v107, v[96:97], off
	s_add_u32 s2, s2, 0x60000
	s_addc_u32 s3, s3, 0
	v_lshl_add_u64 v[96:97], v[48:49], 0, s[2:3]
	v_add_co_u32_e64 v98, s[4:5], s9, v96
	s_nop 1
	v_addc_co_u32_e64 v99, s[4:5], 0, v97, s[4:5]
	global_load_dword v108, v[96:97], off
	v_add_co_u32_e64 v120, s[4:5], s11, v96
	s_nop 1
	v_addc_co_u32_e64 v121, s[4:5], 0, v97, s[4:5]
	v_add_co_u32_e64 v96, s[4:5], s12, v96
	s_nop 1
	v_addc_co_u32_e64 v97, s[4:5], 0, v97, s[4:5]
	global_load_dword v109, v[98:99], off
	global_load_dword v110, v[120:121], off
	global_load_dword v111, v[96:97], off
	s_add_u32 s2, s2, 0x60000
	s_addc_u32 s3, s3, 0
	v_lshl_add_u64 v[96:97], v[48:49], 0, s[2:3]
	v_add_co_u32_e64 v98, s[4:5], s9, v96
	s_nop 1
	v_addc_co_u32_e64 v99, s[4:5], 0, v97, s[4:5]
	global_load_dword v112, v[96:97], off
	v_add_co_u32_e64 v120, s[4:5], s11, v96
	s_nop 1
	v_addc_co_u32_e64 v121, s[4:5], 0, v97, s[4:5]
	v_add_co_u32_e64 v96, s[4:5], s12, v96
	s_nop 1
	v_addc_co_u32_e64 v97, s[4:5], 0, v97, s[4:5]
	global_load_dword v113, v[98:99], off
	global_load_dword v114, v[120:121], off
	global_load_dword v115, v[96:97], off
	s_add_u32 s2, s2, 0x60000
	s_addc_u32 s3, s3, 0
	s_mov_b32 s6, 0x120000
	v_mov_b32_e32 v116, v48
	v_mov_b32_e32 v117, v49
	v_add_co_u32_e64 v116, s[4:5], s6, v116
	s_nop 1
	v_addc_co_u32_e64 v117, s[4:5], 0, v117, s[4:5]
	s_mov_b64 s[2:3], 0
.LBB0_33:
	ds_read_b128 v[18:21], v47
	ds_read_b128 v[2:5], v47 offset:4096
	ds_read_b128 v[22:25], v47 offset:8192
	ds_read_b128 v[6:9], v47 offset:12288
	ds_read_b128 v[26:29], v47 offset:16384
	ds_read_b128 v[10:13], v47 offset:20480
	ds_read_b128 v[30:33], v47 offset:24576
	ds_read_b128 v[14:17], v47 offset:28672
	ds_read_b128 v[34:37], v47 offset:32768
	ds_read_b128 v[68:71], v47 offset:36864
	ds_read_b128 v[72:75], v47 offset:40960
	ds_read_b128 v[76:79], v47 offset:45056
	ds_read_b128 v[80:83], v47 offset:49152
	ds_read_b128 v[84:87], v47 offset:53248
	ds_read_b128 v[88:91], v47 offset:57344
	ds_read_b128 v[92:95], v47 offset:61440
	s_add_u32 s2, s2, 0x60000
	s_addc_u32 s3, s3, 0
	v_add_u32_e32 v47, 16, v47
	s_waitcnt vmcnt(14)
	s_waitcnt lgkmcnt(15)
	v_pk_fma_f32 v[156:157], v[18:19], v[100:101], v[156:157]
	s_waitcnt lgkmcnt(14)
	v_pk_fma_f32 v[158:159], v[2:3], v[100:101], v[158:159]
	s_waitcnt lgkmcnt(13)
	v_pk_fma_f32 v[160:161], v[22:23], v[100:101], v[160:161]
	s_waitcnt lgkmcnt(12)
	v_pk_fma_f32 v[162:163], v[6:7], v[100:101], v[162:163]
	s_waitcnt lgkmcnt(11)
	v_pk_fma_f32 v[164:165], v[26:27], v[100:101], v[164:165]
	s_waitcnt lgkmcnt(10)
	v_pk_fma_f32 v[166:167], v[10:11], v[100:101], v[166:167]
	s_waitcnt lgkmcnt(9)
	v_pk_fma_f32 v[168:169], v[30:31], v[100:101], v[168:169]
	s_waitcnt lgkmcnt(8)
	v_pk_fma_f32 v[170:171], v[14:15], v[100:101], v[170:171]
	s_waitcnt lgkmcnt(7)
	v_pk_fma_f32 v[172:173], v[34:35], v[100:101], v[172:173]
	s_waitcnt lgkmcnt(6)
	v_pk_fma_f32 v[174:175], v[68:69], v[100:101], v[174:175]
	s_waitcnt lgkmcnt(5)
	v_pk_fma_f32 v[176:177], v[72:73], v[100:101], v[176:177]
	s_waitcnt lgkmcnt(4)
	v_pk_fma_f32 v[178:179], v[76:77], v[100:101], v[178:179]
	s_waitcnt lgkmcnt(3)
	v_pk_fma_f32 v[180:181], v[80:81], v[100:101], v[180:181]
	s_waitcnt lgkmcnt(2)
	v_pk_fma_f32 v[182:183], v[84:85], v[100:101], v[182:183]
	s_waitcnt lgkmcnt(1)
	v_pk_fma_f32 v[184:185], v[88:89], v[100:101], v[184:185]
	s_waitcnt lgkmcnt(0)
	v_pk_fma_f32 v[186:187], v[92:93], v[100:101], v[186:187]
	s_waitcnt vmcnt(12)
; __device__ __forceinline__ void phase_prologue(const Params& p, uchar* sm) {
;     ...
;         const float* wp = p.ada_w + (size_t)(w * 128) * NMODV + col;
; #pragma unroll 4
;         for (int k = 0; k < 128; ++k) { const float wv = wp[(size_t)k * NMODV];
; #pragma unroll
;             for (int b = 0; b < 16; ++b) acc[b] += sc[b * 1024 + w * 128 + k] * wv; }
	v_pk_fma_f32 v[156:157], v[20:21], v[102:103], v[156:157]
	v_pk_fma_f32 v[158:159], v[4:5], v[102:103], v[158:159]
	v_pk_fma_f32 v[160:161], v[24:25], v[102:103], v[160:161]
	v_pk_fma_f32 v[162:163], v[8:9], v[102:103], v[162:163]
	v_pk_fma_f32 v[164:165], v[28:29], v[102:103], v[164:165]
	v_pk_fma_f32 v[166:167], v[12:13], v[102:103], v[166:167]
	v_pk_fma_f32 v[168:169], v[32:33], v[102:103], v[168:169]
	v_pk_fma_f32 v[170:171], v[16:17], v[102:103], v[170:171]
	v_pk_fma_f32 v[172:173], v[36:37], v[102:103], v[172:173]
	v_pk_fma_f32 v[174:175], v[70:71], v[102:103], v[174:175]
	v_pk_fma_f32 v[176:177], v[74:75], v[102:103], v[176:177]
	v_pk_fma_f32 v[178:179], v[78:79], v[102:103], v[178:179]
	v_pk_fma_f32 v[180:181], v[82:83], v[102:103], v[180:181]
	v_pk_fma_f32 v[182:183], v[86:87], v[102:103], v[182:183]
	v_pk_fma_f32 v[184:185], v[90:91], v[102:103], v[184:185]
	v_pk_fma_f32 v[186:187], v[94:95], v[102:103], v[186:187]
	v_lshl_add_u64 v[96:97], v[116:117], 0, s[2:3]
	v_add_co_u32_e64 v98, s[4:5], s9, v96
	s_nop 1
	v_addc_co_u32_e64 v99, s[4:5], 0, v97, s[4:5]
	global_load_dword v100, v[96:97], off
	v_add_co_u32_e64 v120, s[4:5], s11, v96
	s_nop 1
	v_addc_co_u32_e64 v121, s[4:5], 0, v97, s[4:5]
	v_add_co_u32_e64 v96, s[4:5], s12, v96
	s_nop 1
	v_addc_co_u32_e64 v97, s[4:5], 0, v97, s[4:5]
	global_load_dword v101, v[98:99], off
	global_load_dword v102, v[120:121], off
	global_load_dword v103, v[96:97], off
	ds_read_b128 v[18:21], v47
	ds_read_b128 v[2:5], v47 offset:4096
	ds_read_b128 v[22:25], v47 offset:8192
	ds_read_b128 v[6:9], v47 offset:12288
	ds_read_b128 v[26:29], v47 offset:16384
	ds_read_b128 v[10:13], v47 offset:20480
	ds_read_b128 v[30:33], v47 offset:24576
	ds_read_b128 v[14:17], v47 offset:28672
	ds_read_b128 v[34:37], v47 offset:32768
	ds_read_b128 v[68:71], v47 offset:36864
	ds_read_b128 v[72:75], v47 offset:40960
	ds_read_b128 v[76:79], v47 offset:45056
	ds_read_b128 v[80:83], v47 offset:49152
	ds_read_b128 v[84:87], v47 offset:53248
	ds_read_b128 v[88:91], v47 offset:57344
	ds_read_b128 v[92:95], v47 offset:61440
	s_add_u32 s2, s2, 0x60000
	s_addc_u32 s3, s3, 0
	v_add_u32_e32 v47, 16, v47
	s_waitcnt vmcnt(14)
	s_waitcnt lgkmcnt(15)
	v_pk_fma_f32 v[156:157], v[18:19], v[104:105], v[156:157]
	s_waitcnt lgkmcnt(14)
	v_pk_fma_f32 v[158:159], v[2:3], v[104:105], v[158:159]
	s_waitcnt lgkmcnt(13)
	v_pk_fma_f32 v[160:161], v[22:23], v[104:105], v[160:161]
	s_waitcnt lgkmcnt(12)
	v_pk_fma_f32 v[162:163], v[6:7], v[104:105], v[162:163]
	s_waitcnt lgkmcnt(11)
	v_pk_fma_f32 v[164:165], v[26:27], v[104:105], v[164:165]
	s_waitcnt lgkmcnt(10)
	v_pk_fma_f32 v[166:167], v[10:11], v[104:105], v[166:167]
	s_waitcnt lgkmcnt(9)
	v_pk_fma_f32 v[168:169], v[30:31], v[104:105], v[168:169]
	s_waitcnt lgkmcnt(8)
	v_pk_fma_f32 v[170:171], v[14:15], v[104:105], v[170:171]
	s_waitcnt lgkmcnt(7)
	v_pk_fma_f32 v[172:173], v[34:35], v[104:105], v[172:173]
	s_waitcnt lgkmcnt(6)
	v_pk_fma_f32 v[174:175], v[68:69], v[104:105], v[174:175]
	s_waitcnt lgkmcnt(5)
	v_pk_fma_f32 v[176:177], v[72:73], v[104:105], v[176:177]
	s_waitcnt lgkmcnt(4)
	v_pk_fma_f32 v[178:179], v[76:77], v[104:105], v[178:179]
	s_waitcnt lgkmcnt(3)
	v_pk_fma_f32 v[180:181], v[80:81], v[104:105], v[180:181]
	s_waitcnt lgkmcnt(2)
	v_pk_fma_f32 v[182:183], v[84:85], v[104:105], v[182:183]
	s_waitcnt lgkmcnt(1)
	v_pk_fma_f32 v[184:185], v[88:89], v[104:105], v[184:185]
	s_waitcnt lgkmcnt(0)
	v_pk_fma_f32 v[186:187], v[92:93], v[104:105], v[186:187]
	s_waitcnt vmcnt(12)
	v_pk_fma_f32 v[156:157], v[20:21], v[106:107], v[156:157]
	v_pk_fma_f32 v[158:159], v[4:5], v[106:107], v[158:159]
	v_pk_fma_f32 v[160:161], v[24:25], v[106:107], v[160:161]
	v_pk_fma_f32 v[162:163], v[8:9], v[106:107], v[162:163]
	v_pk_fma_f32 v[164:165], v[28:29], v[106:107], v[164:165]
	v_pk_fma_f32 v[166:167], v[12:13], v[106:107], v[166:167]
	v_pk_fma_f32 v[168:169], v[32:33], v[106:107], v[168:169]
	v_pk_fma_f32 v[170:171], v[16:17], v[106:107], v[170:171]
	v_pk_fma_f32 v[172:173], v[36:37], v[106:107], v[172:173]
	v_pk_fma_f32 v[174:175], v[70:71], v[106:107], v[174:175]
	v_pk_fma_f32 v[176:177], v[74:75], v[106:107], v[176:177]
	v_pk_fma_f32 v[178:179], v[78:79], v[106:107], v[178:179]
	v_pk_fma_f32 v[180:181], v[82:83], v[106:107], v[180:181]
	v_pk_fma_f32 v[182:183], v[86:87], v[106:107], v[182:183]
	v_pk_fma_f32 v[184:185], v[90:91], v[106:107], v[184:185]
	v_pk_fma_f32 v[186:187], v[94:95], v[106:107], v[186:187]
	v_lshl_add_u64 v[96:97], v[116:117], 0, s[2:3]
	v_add_co_u32_e64 v98, s[4:5], s9, v96
	s_nop 1
	v_addc_co_u32_e64 v99, s[4:5], 0, v97, s[4:5]
	global_load_dword v104, v[96:97], off
	v_add_co_u32_e64 v120, s[4:5], s11, v96
	s_nop 1
	v_addc_co_u32_e64 v121, s[4:5], 0, v97, s[4:5]
	v_add_co_u32_e64 v96, s[4:5], s12, v96
	s_nop 1
	v_addc_co_u32_e64 v97, s[4:5], 0, v97, s[4:5]
	global_load_dword v105, v[98:99], off
	global_load_dword v106, v[120:121], off
	global_load_dword v107, v[96:97], off
	ds_read_b128 v[18:21], v47
	ds_read_b128 v[2:5], v47 offset:4096
	ds_read_b128 v[22:25], v47 offset:8192
	ds_read_b128 v[6:9], v47 offset:12288
	ds_read_b128 v[26:29], v47 offset:16384
	ds_read_b128 v[10:13], v47 offset:20480
	ds_read_b128 v[30:33], v47 offset:24576
	ds_read_b128 v[14:17], v47 offset:28672
	ds_read_b128 v[34:37], v47 offset:32768
	ds_read_b128 v[68:71], v47 offset:36864
	ds_read_b128 v[72:75], v47 offset:40960
	ds_read_b128 v[76:79], v47 offset:45056
	ds_read_b128 v[80:83], v47 offset:49152
	ds_read_b128 v[84:87], v47 offset:53248
	ds_read_b128 v[88:91], v47 offset:57344
	ds_read_b128 v[92:95], v47 offset:61440
	s_add_u32 s2, s2, 0x60000
	s_addc_u32 s3, s3, 0
	v_add_u32_e32 v47, 16, v47
	s_waitcnt vmcnt(14)
; __device__ __forceinline__ void phase_prologue(const Params& p, uchar* sm) {
;     ...
;         const float* wp = p.ada_w + (size_t)(w * 128) * NMODV + col;
; #pragma unroll 4
;         for (int k = 0; k < 128; ++k) { const float wv = wp[(size_t)k * NMODV];
; #pragma unroll
;             for (int b = 0; b < 16; ++b) acc[b] += sc[b * 1024 + w * 128 + k] * wv; }
	s_waitcnt lgkmcnt(15)
	v_pk_fma_f32 v[156:157], v[18:19], v[108:109], v[156:157]
	s_waitcnt lgkmcnt(14)
	v_pk_fma_f32 v[158:159], v[2:3], v[108:109], v[158:159]
	s_waitcnt lgkmcnt(13)
	v_pk_fma_f32 v[160:161], v[22:23], v[108:109], v[160:161]
	s_waitcnt lgkmcnt(12)
	v_pk_fma_f32 v[162:163], v[6:7], v[108:109], v[162:163]
	s_waitcnt lgkmcnt(11)
	v_pk_fma_f32 v[164:165], v[26:27], v[108:109], v[164:165]
	s_waitcnt lgkmcnt(10)
	v_pk_fma_f32 v[166:167], v[10:11], v[108:109], v[166:167]
	s_waitcnt lgkmcnt(9)
	v_pk_fma_f32 v[168:169], v[30:31], v[108:109], v[168:169]
	s_waitcnt lgkmcnt(8)
	v_pk_fma_f32 v[170:171], v[14:15], v[108:109], v[170:171]
	s_waitcnt lgkmcnt(7)
	v_pk_fma_f32 v[172:173], v[34:35], v[108:109], v[172:173]
	s_waitcnt lgkmcnt(6)
	v_pk_fma_f32 v[174:175], v[68:69], v[108:109], v[174:175]
	s_waitcnt lgkmcnt(5)
	v_pk_fma_f32 v[176:177], v[72:73], v[108:109], v[176:177]
	s_waitcnt lgkmcnt(4)
	v_pk_fma_f32 v[178:179], v[76:77], v[108:109], v[178:179]
	s_waitcnt lgkmcnt(3)
	v_pk_fma_f32 v[180:181], v[80:81], v[108:109], v[180:181]
	s_waitcnt lgkmcnt(2)
	v_pk_fma_f32 v[182:183], v[84:85], v[108:109], v[182:183]
	s_waitcnt lgkmcnt(1)
	v_pk_fma_f32 v[184:185], v[88:89], v[108:109], v[184:185]
	s_waitcnt lgkmcnt(0)
	v_pk_fma_f32 v[186:187], v[92:93], v[108:109], v[186:187]
	s_waitcnt vmcnt(12)
	v_pk_fma_f32 v[156:157], v[20:21], v[110:111], v[156:157]
	v_pk_fma_f32 v[158:159], v[4:5], v[110:111], v[158:159]
	v_pk_fma_f32 v[160:161], v[24:25], v[110:111], v[160:161]
	v_pk_fma_f32 v[162:163], v[8:9], v[110:111], v[162:163]
	v_pk_fma_f32 v[164:165], v[28:29], v[110:111], v[164:165]
	v_pk_fma_f32 v[166:167], v[12:13], v[110:111], v[166:167]
	v_pk_fma_f32 v[168:169], v[32:33], v[110:111], v[168:169]
	v_pk_fma_f32 v[170:171], v[16:17], v[110:111], v[170:171]
	v_pk_fma_f32 v[172:173], v[36:37], v[110:111], v[172:173]
	v_pk_fma_f32 v[174:175], v[70:71], v[110:111], v[174:175]
	v_pk_fma_f32 v[176:177], v[74:75], v[110:111], v[176:177]
	v_pk_fma_f32 v[178:179], v[78:79], v[110:111], v[178:179]
	v_pk_fma_f32 v[180:181], v[82:83], v[110:111], v[180:181]
	v_pk_fma_f32 v[182:183], v[86:87], v[110:111], v[182:183]
	v_pk_fma_f32 v[184:185], v[90:91], v[110:111], v[184:185]
	v_pk_fma_f32 v[186:187], v[94:95], v[110:111], v[186:187]
	v_lshl_add_u64 v[96:97], v[116:117], 0, s[2:3]
	v_add_co_u32_e64 v98, s[4:5], s9, v96
	s_nop 1
	v_addc_co_u32_e64 v99, s[4:5], 0, v97, s[4:5]
	global_load_dword v108, v[96:97], off
	v_add_co_u32_e64 v120, s[4:5], s11, v96
	s_nop 1
	v_addc_co_u32_e64 v121, s[4:5], 0, v97, s[4:5]
	v_add_co_u32_e64 v96, s[4:5], s12, v96
	s_nop 1
	v_addc_co_u32_e64 v97, s[4:5], 0, v97, s[4:5]
	global_load_dword v109, v[98:99], off
	global_load_dword v110, v[120:121], off
	global_load_dword v111, v[96:97], off
	ds_read_b128 v[18:21], v47
	ds_read_b128 v[2:5], v47 offset:4096
	ds_read_b128 v[22:25], v47 offset:8192
	ds_read_b128 v[6:9], v47 offset:12288
	ds_read_b128 v[26:29], v47 offset:16384
	ds_read_b128 v[10:13], v47 offset:20480
	ds_read_b128 v[30:33], v47 offset:24576
	ds_read_b128 v[14:17], v47 offset:28672
	ds_read_b128 v[34:37], v47 offset:32768
	ds_read_b128 v[68:71], v47 offset:36864
	ds_read_b128 v[72:75], v47 offset:40960
	ds_read_b128 v[76:79], v47 offset:45056
	ds_read_b128 v[80:83], v47 offset:49152
	ds_read_b128 v[84:87], v47 offset:53248
	ds_read_b128 v[88:91], v47 offset:57344
	ds_read_b128 v[92:95], v47 offset:61440
	s_add_u32 s2, s2, 0x60000
	s_addc_u32 s3, s3, 0
	v_add_u32_e32 v47, 16, v47
	s_waitcnt vmcnt(14)
	s_waitcnt lgkmcnt(15)
	v_pk_fma_f32 v[156:157], v[18:19], v[112:113], v[156:157]
	s_waitcnt lgkmcnt(14)
	v_pk_fma_f32 v[158:159], v[2:3], v[112:113], v[158:159]
	s_waitcnt lgkmcnt(13)
	v_pk_fma_f32 v[160:161], v[22:23], v[112:113], v[160:161]
	s_waitcnt lgkmcnt(12)
	v_pk_fma_f32 v[162:163], v[6:7], v[112:113], v[162:163]
	s_waitcnt lgkmcnt(11)
	v_pk_fma_f32 v[164:165], v[26:27], v[112:113], v[164:165]
	s_waitcnt lgkmcnt(10)
	v_pk_fma_f32 v[166:167], v[10:11], v[112:113], v[166:167]
	s_waitcnt lgkmcnt(9)
	v_pk_fma_f32 v[168:169], v[30:31], v[112:113], v[168:169]
	s_waitcnt lgkmcnt(8)
	v_pk_fma_f32 v[170:171], v[14:15], v[112:113], v[170:171]
	s_waitcnt lgkmcnt(7)
	v_pk_fma_f32 v[172:173], v[34:35], v[112:113], v[172:173]
	s_waitcnt lgkmcnt(6)
	v_pk_fma_f32 v[174:175], v[68:69], v[112:113], v[174:175]
	s_waitcnt lgkmcnt(5)
	v_pk_fma_f32 v[176:177], v[72:73], v[112:113], v[176:177]
	s_waitcnt lgkmcnt(4)
	v_pk_fma_f32 v[178:179], v[76:77], v[112:113], v[178:179]
	s_waitcnt lgkmcnt(3)
	v_pk_fma_f32 v[180:181], v[80:81], v[112:113], v[180:181]
	s_waitcnt lgkmcnt(2)
	v_pk_fma_f32 v[182:183], v[84:85], v[112:113], v[182:183]
	s_waitcnt lgkmcnt(1)
	v_pk_fma_f32 v[184:185], v[88:89], v[112:113], v[184:185]
	s_waitcnt lgkmcnt(0)
	v_pk_fma_f32 v[186:187], v[92:93], v[112:113], v[186:187]
	s_waitcnt vmcnt(12)
	v_pk_fma_f32 v[156:157], v[20:21], v[114:115], v[156:157]
	v_pk_fma_f32 v[158:159], v[4:5], v[114:115], v[158:159]
	v_pk_fma_f32 v[160:161], v[24:25], v[114:115], v[160:161]
	v_pk_fma_f32 v[162:163], v[8:9], v[114:115], v[162:163]
	v_pk_fma_f32 v[164:165], v[28:29], v[114:115], v[164:165]
	v_pk_fma_f32 v[166:167], v[12:13], v[114:115], v[166:167]
	v_pk_fma_f32 v[168:169], v[32:33], v[114:115], v[168:169]
	v_pk_fma_f32 v[170:171], v[16:17], v[114:115], v[170:171]
	v_pk_fma_f32 v[172:173], v[36:37], v[114:115], v[172:173]
	v_pk_fma_f32 v[174:175], v[70:71], v[114:115], v[174:175]
	v_pk_fma_f32 v[176:177], v[74:75], v[114:115], v[176:177]
	v_pk_fma_f32 v[178:179], v[78:79], v[114:115], v[178:179]
	v_pk_fma_f32 v[180:181], v[82:83], v[114:115], v[180:181]
	v_pk_fma_f32 v[182:183], v[86:87], v[114:115], v[182:183]
	v_pk_fma_f32 v[184:185], v[90:91], v[114:115], v[184:185]
	v_pk_fma_f32 v[186:187], v[94:95], v[114:115], v[186:187]
	v_lshl_add_u64 v[96:97], v[116:117], 0, s[2:3]
	v_add_co_u32_e64 v98, s[4:5], s9, v96
	s_nop 1
	v_addc_co_u32_e64 v99, s[4:5], 0, v97, s[4:5]
	global_load_dword v112, v[96:97], off
	v_add_co_u32_e64 v120, s[4:5], s11, v96
	s_nop 1
	v_addc_co_u32_e64 v121, s[4:5], 0, v97, s[4:5]
	v_add_co_u32_e64 v96, s[4:5], s12, v96
	s_nop 1
	v_addc_co_u32_e64 v97, s[4:5], 0, v97, s[4:5]
	global_load_dword v113, v[98:99], off
	global_load_dword v114, v[120:121], off
	global_load_dword v115, v[96:97], off
	s_cmp_lg_u32 s2, 0xa80000
	s_cbranch_scc1 .LBB0_33
; __device__ __forceinline__ void phase_prologue(const Params& p, uchar* sm) {
;     ...
;         const float* wp = p.ada_w + (size_t)(w * 128) * NMODV + col;
; #pragma unroll 4
;         for (int k = 0; k < 128; ++k) { const float wv = wp[(size_t)k * NMODV];
; #pragma unroll
;             for (int b = 0; b < 16; ++b) acc[b] += sc[b * 1024 + w * 128 + k] * wv; }
	ds_read_b128 v[18:21], v47
	ds_read_b128 v[2:5], v47 offset:4096
	ds_read_b128 v[22:25], v47 offset:8192
	ds_read_b128 v[6:9], v47 offset:12288
	ds_read_b128 v[26:29], v47 offset:16384
	ds_read_b128 v[10:13], v47 offset:20480
	ds_read_b128 v[30:33], v47 offset:24576
	ds_read_b128 v[14:17], v47 offset:28672
	ds_read_b128 v[34:37], v47 offset:32768
	ds_read_b128 v[68:71], v47 offset:36864
	ds_read_b128 v[72:75], v47 offset:40960
	ds_read_b128 v[76:79], v47 offset:45056
	ds_read_b128 v[80:83], v47 offset:49152
	ds_read_b128 v[84:87], v47 offset:53248
	ds_read_b128 v[88:91], v47 offset:57344
	ds_read_b128 v[92:95], v47 offset:61440
	s_add_u32 s2, s2, 0x60000
	s_addc_u32 s3, s3, 0
	v_add_u32_e32 v47, 16, v47
	s_waitcnt vmcnt(14)
	s_waitcnt lgkmcnt(15)
	v_pk_fma_f32 v[156:157], v[18:19], v[100:101], v[156:157]
	s_waitcnt lgkmcnt(14)
	v_pk_fma_f32 v[158:159], v[2:3], v[100:101], v[158:159]
	s_waitcnt lgkmcnt(13)
	v_pk_fma_f32 v[160:161], v[22:23], v[100:101], v[160:161]
	s_waitcnt lgkmcnt(12)
	v_pk_fma_f32 v[162:163], v[6:7], v[100:101], v[162:163]
	s_waitcnt lgkmcnt(11)
	v_pk_fma_f32 v[164:165], v[26:27], v[100:101], v[164:165]
	s_waitcnt lgkmcnt(10)
	v_pk_fma_f32 v[166:167], v[10:11], v[100:101], v[166:167]
	s_waitcnt lgkmcnt(9)
	v_pk_fma_f32 v[168:169], v[30:31], v[100:101], v[168:169]
	s_waitcnt lgkmcnt(8)
	v_pk_fma_f32 v[170:171], v[14:15], v[100:101], v[170:171]
	s_waitcnt lgkmcnt(7)
	v_pk_fma_f32 v[172:173], v[34:35], v[100:101], v[172:173]
	s_waitcnt lgkmcnt(6)
	v_pk_fma_f32 v[174:175], v[68:69], v[100:101], v[174:175]
	s_waitcnt lgkmcnt(5)
	v_pk_fma_f32 v[176:177], v[72:73], v[100:101], v[176:177]
	s_waitcnt lgkmcnt(4)
	v_pk_fma_f32 v[178:179], v[76:77], v[100:101], v[178:179]
	s_waitcnt lgkmcnt(3)
	v_pk_fma_f32 v[180:181], v[80:81], v[100:101], v[180:181]
	s_waitcnt lgkmcnt(2)
	v_pk_fma_f32 v[182:183], v[84:85], v[100:101], v[182:183]
	s_waitcnt lgkmcnt(1)
	v_pk_fma_f32 v[184:185], v[88:89], v[100:101], v[184:185]
	s_waitcnt lgkmcnt(0)
	v_pk_fma_f32 v[186:187], v[92:93], v[100:101], v[186:187]
	s_waitcnt vmcnt(12)
	v_pk_fma_f32 v[156:157], v[20:21], v[102:103], v[156:157]
	v_pk_fma_f32 v[158:159], v[4:5], v[102:103], v[158:159]
	v_pk_fma_f32 v[160:161], v[24:25], v[102:103], v[160:161]
	v_pk_fma_f32 v[162:163], v[8:9], v[102:103], v[162:163]
	v_pk_fma_f32 v[164:165], v[28:29], v[102:103], v[164:165]
	v_pk_fma_f32 v[166:167], v[12:13], v[102:103], v[166:167]
	v_pk_fma_f32 v[168:169], v[32:33], v[102:103], v[168:169]
	v_pk_fma_f32 v[170:171], v[16:17], v[102:103], v[170:171]
	v_pk_fma_f32 v[172:173], v[36:37], v[102:103], v[172:173]
	v_pk_fma_f32 v[174:175], v[70:71], v[102:103], v[174:175]
	v_pk_fma_f32 v[176:177], v[74:75], v[102:103], v[176:177]
	v_pk_fma_f32 v[178:179], v[78:79], v[102:103], v[178:179]
	v_pk_fma_f32 v[180:181], v[82:83], v[102:103], v[180:181]
	v_pk_fma_f32 v[182:183], v[86:87], v[102:103], v[182:183]
	v_pk_fma_f32 v[184:185], v[90:91], v[102:103], v[184:185]
	v_pk_fma_f32 v[186:187], v[94:95], v[102:103], v[186:187]
	ds_read_b128 v[18:21], v47
	ds_read_b128 v[2:5], v47 offset:4096
	ds_read_b128 v[22:25], v47 offset:8192
	ds_read_b128 v[6:9], v47 offset:12288
	ds_read_b128 v[26:29], v47 offset:16384
	ds_read_b128 v[10:13], v47 offset:20480
	ds_read_b128 v[30:33], v47 offset:24576
	ds_read_b128 v[14:17], v47 offset:28672
	ds_read_b128 v[34:37], v47 offset:32768
	ds_read_b128 v[68:71], v47 offset:36864
	ds_read_b128 v[72:75], v47 offset:40960
	ds_read_b128 v[76:79], v47 offset:45056
	ds_read_b128 v[80:83], v47 offset:49152
	ds_read_b128 v[84:87], v47 offset:53248
	ds_read_b128 v[88:91], v47 offset:57344
	ds_read_b128 v[92:95], v47 offset:61440
	s_add_u32 s2, s2, 0x60000
	s_addc_u32 s3, s3, 0
	v_add_u32_e32 v47, 16, v47
	s_waitcnt vmcnt(10)
	s_waitcnt lgkmcnt(15)
	v_pk_fma_f32 v[156:157], v[18:19], v[104:105], v[156:157]
	s_waitcnt lgkmcnt(14)
	v_pk_fma_f32 v[158:159], v[2:3], v[104:105], v[158:159]
	s_waitcnt lgkmcnt(13)
	v_pk_fma_f32 v[160:161], v[22:23], v[104:105], v[160:161]
	s_waitcnt lgkmcnt(12)
	v_pk_fma_f32 v[162:163], v[6:7], v[104:105], v[162:163]
	s_waitcnt lgkmcnt(11)
	v_pk_fma_f32 v[164:165], v[26:27], v[104:105], v[164:165]
	s_waitcnt lgkmcnt(10)
	v_pk_fma_f32 v[166:167], v[10:11], v[104:105], v[166:167]
	s_waitcnt lgkmcnt(9)
	v_pk_fma_f32 v[168:169], v[30:31], v[104:105], v[168:169]
	s_waitcnt lgkmcnt(8)
	v_pk_fma_f32 v[170:171], v[14:15], v[104:105], v[170:171]
	s_waitcnt lgkmcnt(7)
	v_pk_fma_f32 v[172:173], v[34:35], v[104:105], v[172:173]
	s_waitcnt lgkmcnt(6)
	v_pk_fma_f32 v[174:175], v[68:69], v[104:105], v[174:175]
	s_waitcnt lgkmcnt(5)
	v_pk_fma_f32 v[176:177], v[72:73], v[104:105], v[176:177]
	s_waitcnt lgkmcnt(4)
	v_pk_fma_f32 v[178:179], v[76:77], v[104:105], v[178:179]
	s_waitcnt lgkmcnt(3)
	v_pk_fma_f32 v[180:181], v[80:81], v[104:105], v[180:181]
	s_waitcnt lgkmcnt(2)
	v_pk_fma_f32 v[182:183], v[84:85], v[104:105], v[182:183]
	s_waitcnt lgkmcnt(1)
	v_pk_fma_f32 v[184:185], v[88:89], v[104:105], v[184:185]
	s_waitcnt lgkmcnt(0)
	v_pk_fma_f32 v[186:187], v[92:93], v[104:105], v[186:187]
	s_waitcnt vmcnt(8)
; __device__ __forceinline__ void phase_prologue(const Params& p, uchar* sm) {
;     ...
;         const float* wp = p.ada_w + (size_t)(w * 128) * NMODV + col;
; #pragma unroll 4
;         for (int k = 0; k < 128; ++k) { const float wv = wp[(size_t)k * NMODV];
; #pragma unroll
;             for (int b = 0; b < 16; ++b) acc[b] += sc[b * 1024 + w * 128 + k] * wv; }
	v_pk_fma_f32 v[156:157], v[20:21], v[106:107], v[156:157]
	v_pk_fma_f32 v[158:159], v[4:5], v[106:107], v[158:159]
	v_pk_fma_f32 v[160:161], v[24:25], v[106:107], v[160:161]
	v_pk_fma_f32 v[162:163], v[8:9], v[106:107], v[162:163]
	v_pk_fma_f32 v[164:165], v[28:29], v[106:107], v[164:165]
	v_pk_fma_f32 v[166:167], v[12:13], v[106:107], v[166:167]
	v_pk_fma_f32 v[168:169], v[32:33], v[106:107], v[168:169]
	v_pk_fma_f32 v[170:171], v[16:17], v[106:107], v[170:171]
	v_pk_fma_f32 v[172:173], v[36:37], v[106:107], v[172:173]
	v_pk_fma_f32 v[174:175], v[70:71], v[106:107], v[174:175]
	v_pk_fma_f32 v[176:177], v[74:75], v[106:107], v[176:177]
	v_pk_fma_f32 v[178:179], v[78:79], v[106:107], v[178:179]
	v_pk_fma_f32 v[180:181], v[82:83], v[106:107], v[180:181]
	v_pk_fma_f32 v[182:183], v[86:87], v[106:107], v[182:183]
	v_pk_fma_f32 v[184:185], v[90:91], v[106:107], v[184:185]
	v_pk_fma_f32 v[186:187], v[94:95], v[106:107], v[186:187]
	ds_read_b128 v[18:21], v47
	ds_read_b128 v[2:5], v47 offset:4096
	ds_read_b128 v[22:25], v47 offset:8192
	ds_read_b128 v[6:9], v47 offset:12288
	ds_read_b128 v[26:29], v47 offset:16384
	ds_read_b128 v[10:13], v47 offset:20480
	ds_read_b128 v[30:33], v47 offset:24576
	ds_read_b128 v[14:17], v47 offset:28672
	ds_read_b128 v[34:37], v47 offset:32768
	ds_read_b128 v[68:71], v47 offset:36864
	ds_read_b128 v[72:75], v47 offset:40960
	ds_read_b128 v[76:79], v47 offset:45056
	ds_read_b128 v[80:83], v47 offset:49152
	ds_read_b128 v[84:87], v47 offset:53248
	ds_read_b128 v[88:91], v47 offset:57344
	ds_read_b128 v[92:95], v47 offset:61440
	s_add_u32 s2, s2, 0x60000
	s_addc_u32 s3, s3, 0
	v_add_u32_e32 v47, 16, v47
	s_waitcnt vmcnt(6)
	s_waitcnt lgkmcnt(15)
	v_pk_fma_f32 v[156:157], v[18:19], v[108:109], v[156:157]
	s_waitcnt lgkmcnt(14)
	v_pk_fma_f32 v[158:159], v[2:3], v[108:109], v[158:159]
	s_waitcnt lgkmcnt(13)
	v_pk_fma_f32 v[160:161], v[22:23], v[108:109], v[160:161]
	s_waitcnt lgkmcnt(12)
	v_pk_fma_f32 v[162:163], v[6:7], v[108:109], v[162:163]
	s_waitcnt lgkmcnt(11)
	v_pk_fma_f32 v[164:165], v[26:27], v[108:109], v[164:165]
	s_waitcnt lgkmcnt(10)
	v_pk_fma_f32 v[166:167], v[10:11], v[108:109], v[166:167]
	s_waitcnt lgkmcnt(9)
	v_pk_fma_f32 v[168:169], v[30:31], v[108:109], v[168:169]
	s_waitcnt lgkmcnt(8)
	v_pk_fma_f32 v[170:171], v[14:15], v[108:109], v[170:171]
	s_waitcnt lgkmcnt(7)
	v_pk_fma_f32 v[172:173], v[34:35], v[108:109], v[172:173]
	s_waitcnt lgkmcnt(6)
	v_pk_fma_f32 v[174:175], v[68:69], v[108:109], v[174:175]
	s_waitcnt lgkmcnt(5)
	v_pk_fma_f32 v[176:177], v[72:73], v[108:109], v[176:177]
	s_waitcnt lgkmcnt(4)
	v_pk_fma_f32 v[178:179], v[76:77], v[108:109], v[178:179]
	s_waitcnt lgkmcnt(3)
	v_pk_fma_f32 v[180:181], v[80:81], v[108:109], v[180:181]
	s_waitcnt lgkmcnt(2)
	v_pk_fma_f32 v[182:183], v[84:85], v[108:109], v[182:183]
	s_waitcnt lgkmcnt(1)
	v_pk_fma_f32 v[184:185], v[88:89], v[108:109], v[184:185]
	s_waitcnt lgkmcnt(0)
	v_pk_fma_f32 v[186:187], v[92:93], v[108:109], v[186:187]
	s_waitcnt vmcnt(4)
	v_pk_fma_f32 v[156:157], v[20:21], v[110:111], v[156:157]
	v_pk_fma_f32 v[158:159], v[4:5], v[110:111], v[158:159]
	v_pk_fma_f32 v[160:161], v[24:25], v[110:111], v[160:161]
	v_pk_fma_f32 v[162:163], v[8:9], v[110:111], v[162:163]
	v_pk_fma_f32 v[164:165], v[28:29], v[110:111], v[164:165]
	v_pk_fma_f32 v[166:167], v[12:13], v[110:111], v[166:167]
	v_pk_fma_f32 v[168:169], v[32:33], v[110:111], v[168:169]
	v_pk_fma_f32 v[170:171], v[16:17], v[110:111], v[170:171]
	v_pk_fma_f32 v[172:173], v[36:37], v[110:111], v[172:173]
	v_pk_fma_f32 v[174:175], v[70:71], v[110:111], v[174:175]
	v_pk_fma_f32 v[176:177], v[74:75], v[110:111], v[176:177]
	v_pk_fma_f32 v[178:179], v[78:79], v[110:111], v[178:179]
	v_pk_fma_f32 v[180:181], v[82:83], v[110:111], v[180:181]
	v_pk_fma_f32 v[182:183], v[86:87], v[110:111], v[182:183]
	v_pk_fma_f32 v[184:185], v[90:91], v[110:111], v[184:185]
	v_pk_fma_f32 v[186:187], v[94:95], v[110:111], v[186:187]
	ds_read_b128 v[18:21], v47
	ds_read_b128 v[2:5], v47 offset:4096
	ds_read_b128 v[22:25], v47 offset:8192
	ds_read_b128 v[6:9], v47 offset:12288
	ds_read_b128 v[26:29], v47 offset:16384
	ds_read_b128 v[10:13], v47 offset:20480
	ds_read_b128 v[30:33], v47 offset:24576
	ds_read_b128 v[14:17], v47 offset:28672
	ds_read_b128 v[34:37], v47 offset:32768
	ds_read_b128 v[68:71], v47 offset:36864
	ds_read_b128 v[72:75], v47 offset:40960
	ds_read_b128 v[76:79], v47 offset:45056
	ds_read_b128 v[80:83], v47 offset:49152
	ds_read_b128 v[84:87], v47 offset:53248
	ds_read_b128 v[88:91], v47 offset:57344
	ds_read_b128 v[92:95], v47 offset:61440
	s_add_u32 s2, s2, 0x60000
	s_addc_u32 s3, s3, 0
	v_add_u32_e32 v47, 16, v47
	s_waitcnt vmcnt(2)
; __device__ __forceinline__ void phase_prologue(const Params& p, uchar* sm) {
;     ...
;         const float* wp = p.ada_w + (size_t)(w * 128) * NMODV + col;
; #pragma unroll 4
;         for (int k = 0; k < 128; ++k) { const float wv = wp[(size_t)k * NMODV];
; #pragma unroll
;             for (int b = 0; b < 16; ++b) acc[b] += sc[b * 1024 + w * 128 + k] * wv; }
; #pragma unroll
;         for (int b = 0; b < 16; ++b) red[(w * 16 + b) * 64 + lane] = acc[b];
;         __syncthreads();
;         for (int o = tid; o < 1024; o += 512) { const int b = o >> 6, cl = o & 63; float s = p.ada_b[item * 64 + cl];
	s_waitcnt lgkmcnt(15)
	v_pk_fma_f32 v[156:157], v[18:19], v[112:113], v[156:157]
	s_waitcnt lgkmcnt(14)
	v_pk_fma_f32 v[158:159], v[2:3], v[112:113], v[158:159]
	s_waitcnt lgkmcnt(13)
	v_pk_fma_f32 v[160:161], v[22:23], v[112:113], v[160:161]
	s_waitcnt lgkmcnt(12)
	v_pk_fma_f32 v[162:163], v[6:7], v[112:113], v[162:163]
	s_waitcnt lgkmcnt(11)
	v_pk_fma_f32 v[164:165], v[26:27], v[112:113], v[164:165]
	s_waitcnt lgkmcnt(10)
	v_pk_fma_f32 v[166:167], v[10:11], v[112:113], v[166:167]
	s_waitcnt lgkmcnt(9)
	v_pk_fma_f32 v[168:169], v[30:31], v[112:113], v[168:169]
	s_waitcnt lgkmcnt(8)
	v_pk_fma_f32 v[170:171], v[14:15], v[112:113], v[170:171]
	s_waitcnt lgkmcnt(7)
	v_pk_fma_f32 v[172:173], v[34:35], v[112:113], v[172:173]
	s_waitcnt lgkmcnt(6)
	v_pk_fma_f32 v[174:175], v[68:69], v[112:113], v[174:175]
	s_waitcnt lgkmcnt(5)
	v_pk_fma_f32 v[176:177], v[72:73], v[112:113], v[176:177]
	s_waitcnt lgkmcnt(4)
	v_pk_fma_f32 v[178:179], v[76:77], v[112:113], v[178:179]
	s_waitcnt lgkmcnt(3)
	v_pk_fma_f32 v[180:181], v[80:81], v[112:113], v[180:181]
	s_waitcnt lgkmcnt(2)
	v_pk_fma_f32 v[182:183], v[84:85], v[112:113], v[182:183]
	s_waitcnt lgkmcnt(1)
	v_pk_fma_f32 v[184:185], v[88:89], v[112:113], v[184:185]
	s_waitcnt lgkmcnt(0)
	v_pk_fma_f32 v[186:187], v[92:93], v[112:113], v[186:187]
	s_waitcnt vmcnt(0)
	v_pk_fma_f32 v[156:157], v[20:21], v[114:115], v[156:157]
	v_pk_fma_f32 v[158:159], v[4:5], v[114:115], v[158:159]
	v_pk_fma_f32 v[160:161], v[24:25], v[114:115], v[160:161]
	v_pk_fma_f32 v[162:163], v[8:9], v[114:115], v[162:163]
	v_pk_fma_f32 v[164:165], v[28:29], v[114:115], v[164:165]
	v_pk_fma_f32 v[166:167], v[12:13], v[114:115], v[166:167]
	v_pk_fma_f32 v[168:169], v[32:33], v[114:115], v[168:169]
	v_pk_fma_f32 v[170:171], v[16:17], v[114:115], v[170:171]
	v_pk_fma_f32 v[172:173], v[36:37], v[114:115], v[172:173]
	v_pk_fma_f32 v[174:175], v[70:71], v[114:115], v[174:175]
	v_pk_fma_f32 v[176:177], v[74:75], v[114:115], v[176:177]
	v_pk_fma_f32 v[178:179], v[78:79], v[114:115], v[178:179]
	v_pk_fma_f32 v[180:181], v[82:83], v[114:115], v[180:181]
	v_pk_fma_f32 v[182:183], v[86:87], v[114:115], v[182:183]
	v_pk_fma_f32 v[184:185], v[90:91], v[114:115], v[184:185]
	v_pk_fma_f32 v[186:187], v[94:95], v[114:115], v[186:187]
	v_add_f32_e32 v52, v156, v157
	v_add_f32_e32 v53, v158, v159
	v_add_f32_e32 v54, v160, v161
	v_add_f32_e32 v55, v162, v163
	v_add_f32_e32 v56, v164, v165
	v_add_f32_e32 v57, v166, v167
	v_add_f32_e32 v58, v168, v169
	v_add_f32_e32 v59, v170, v171
	v_add_f32_e32 v60, v172, v173
	v_add_f32_e32 v61, v174, v175
	v_add_f32_e32 v62, v176, v177
	v_add_f32_e32 v63, v178, v179
	v_add_f32_e32 v64, v180, v181
	v_add_f32_e32 v65, v182, v183
	v_add_f32_e32 v50, v184, v185
	v_add_f32_e32 v51, v186, v187
	ds_write2st64_b32 v40, v52, v53 offset1:1
	ds_write2st64_b32 v40, v54, v55 offset0:2 offset1:3
	ds_write2st64_b32 v40, v56, v57 offset0:4 offset1:5
	ds_write2st64_b32 v40, v58, v59 offset0:6 offset1:7
	ds_write2st64_b32 v40, v60, v61 offset0:8 offset1:9
	ds_write2st64_b32 v40, v62, v63 offset0:10 offset1:11
	ds_write2st64_b32 v40, v64, v65 offset0:12 offset1:13
	ds_write2st64_b32 v40, v50, v51 offset0:14 offset1:15
	s_waitcnt lgkmcnt(0)
	s_barrier
	s_and_saveexec_b64 s[2:3], vcc
	s_cbranch_execz .LBB0_31
	s_load_dwordx16 s[76:91], s[0:1], 0x0
	s_lshl_b32 s4, s8, 6
	v_or_b32_e32 v2, s4, v1
	v_ashrrev_i32_e32 v3, 31, v2
	s_ashr_i32 s5, s4, 31
	s_waitcnt lgkmcnt(0)
	v_lshl_add_u64 v[2:3], v[2:3], 2, s[82:83]
	v_lshl_add_u64 v[4:5], s[4:5], 2, v[42:43]
	s_mov_b64 s[6:7], 0
	v_mov_b32_e32 v6, v38
